# block-start latency: selected-mode block 0 and the window mode's first two blocks are LDS-DMA'd ahead (behind the mask set-up / the selected-mode epilogue)
# baseline (speedup 1.0000x reference)
; #define NSA_LD1(jj) do { kr = *(const bf16x8*)((const char*)Kt + (size_t)(jj) * 8192 + kgo); vr = *(const bf16x8*)((const char*)Vt + (jj) * 128 + vgo); } while (0)
; #define NSA_ST1(st_, half_) do { LAS bf16_t* nx_ = stage + (st_) * 18432 + (half_) * 9216 + soff; *(LAS bf16x8*)nx_ = kr; *(LAS bf16x8*)(nx_ + 4608) = vr; } while (0)
; template <int MODE> ...
;     ...
;     if (MODE == 0 && tid < 256) { const int tok = tid >> 2, word = tid & 3; unsigned m = 0u;
;         if (qb < 16) m = word == 0 ? ((2u << qb) - 1u) : 0u;
;         else {
; #pragma unroll
;             for (int n = 0; n < 16; ++n) { const int j = selall[tok * 16 + n]; m |= ((j >> 5) == word) ? (1u << (j & 31)) : 0u; } }
;         masks[tid] = m; }
;     ...
;     bf16x8 kr, vr;
;     NSA_LD1(j0); NSA_ST1(0, 0);
;     if (j0 + 1 <= qb) { NSA_LD1(j0 + 1); NSA_ST1(0, 1); }
.Ltopk_done_q1:
	s_nop 0
	s_waitcnt lgkmcnt(0)
	s_waitcnt vmcnt(0) lgkmcnt(0)
	s_barrier
	v_lshrrev_b32_e32 v92, 3, v184
	v_and_b32_e32 v93, 7, v184
	s_lshr_b32 s0, s80, 3
	s_and_b32 s1, s0, 1
	s_lshl_b32 s1, s1, 2
	v_and_b32_e32 v94, 3, v92
	v_or_b32_e32 v94, s1, v94
	v_xor_b32_e32 v94, v93, v94
	v_add_u32_e32 v95, s80, v92
	v_lshlrev_b32_e32 v174, 7, v95
	v_lshl_add_u32 v174, v94, 4, v174
	v_xor_b32_e32 v94, v93, v92
	v_lshlrev_b32_e32 v175, 14, v95
	v_lshl_add_u32 v175, v94, 4, v175
	s_add_u32 s66, s30, 0x33900000
	s_addc_u32 s67, s31, 0
	s_add_u32 s68, s30, 0x34900000
	s_addc_u32 s69, s31, 0
	s_lshr_b32 s15, s97, 13
	s_lshl_b32 s15, s15, 2
	s_and_b32 s1, s88, 3
	s_or_b32 s15, s15, s1
	s_lshl_b32 s15, s15, 20
	s_add_u32 s66, s66, s15
	s_addc_u32 s67, s67, 0
	s_add_u32 s68, s68, s15
	s_addc_u32 s69, s69, 0
	s_lshl_b32 s33, s80, 7
	s_add_i32 s33, s33, 56384
	s_mov_b32 s14, 0
	s_and_b32 s0, s14, 3
	s_lshl_b32 s0, s0, 14
	s_add_i32 s0, s0, s33
	s_lshl_b32 s1, s14, 13
	s_add_u32 s70, s66, s1
	s_addc_u32 s71, s67, 0
	s_mov_b32 m0, s0
	s_lshl_b32 s1, s14, 7
	global_load_lds_dwordx4 v174, s[70:71]
	s_add_u32 s70, s68, s1
	s_addc_u32 s71, s69, 0
	s_add_i32 m0, s0, 8192
	s_add_i32 s1, s14, 0
	global_load_lds_dwordx4 v175, s[70:71]
	v_cmp_gt_u32_e32 vcc, 0x100, v183
	s_nop 0
	s_and_saveexec_b64 s[20:21], vcc
	s_cbranch_execz .Lnsa_mskip_3
	v_and_b32_e32 v90, 3, v183
	s_cmp_lt_i32 s18, 16
	s_cbranch_scc1 .Lnsa_msmall_1
	v_lshlrev_b32_e32 v91, 4, v183
	v_and_b32_e32 v91, 0xffffffc0, v91
	ds_read_b128 v[50:53], v91 offset:51264
	ds_read_b128 v[54:57], v91 offset:51280
	ds_read_b128 v[58:61], v91 offset:51296
	ds_read_b128 v[62:65], v91 offset:51312
	v_mov_b32_e32 v89, 0
	s_waitcnt lgkmcnt(3)
	v_ashrrev_i32_e32 v82, 5, v50
	v_lshlrev_b32_e64 v83, v50, 1
	v_cmp_eq_u32_e32 vcc, v82, v90
	s_nop 1
	v_cndmask_b32_e32 v83, 0, v83, vcc
	v_or_b32_e32 v89, v89, v83
	v_ashrrev_i32_e32 v82, 5, v51
	v_lshlrev_b32_e64 v83, v51, 1
	v_cmp_eq_u32_e32 vcc, v82, v90
	s_nop 1
	v_cndmask_b32_e32 v83, 0, v83, vcc
	v_or_b32_e32 v89, v89, v83
	v_ashrrev_i32_e32 v82, 5, v52
	v_lshlrev_b32_e64 v83, v52, 1
	v_cmp_eq_u32_e32 vcc, v82, v90
	s_nop 1
	v_cndmask_b32_e32 v83, 0, v83, vcc
	v_or_b32_e32 v89, v89, v83
	v_ashrrev_i32_e32 v82, 5, v53
	v_lshlrev_b32_e64 v83, v53, 1
	v_cmp_eq_u32_e32 vcc, v82, v90
	s_nop 1
	v_cndmask_b32_e32 v83, 0, v83, vcc
	v_or_b32_e32 v89, v89, v83
	s_waitcnt lgkmcnt(2)
	v_ashrrev_i32_e32 v82, 5, v54
	v_lshlrev_b32_e64 v83, v54, 1
	v_cmp_eq_u32_e32 vcc, v82, v90
	s_nop 1
	v_cndmask_b32_e32 v83, 0, v83, vcc
	v_or_b32_e32 v89, v89, v83
	v_ashrrev_i32_e32 v82, 5, v55
	v_lshlrev_b32_e64 v83, v55, 1
	v_cmp_eq_u32_e32 vcc, v82, v90
	s_nop 1
	v_cndmask_b32_e32 v83, 0, v83, vcc
	v_or_b32_e32 v89, v89, v83
	v_ashrrev_i32_e32 v82, 5, v56
	v_lshlrev_b32_e64 v83, v56, 1
	v_cmp_eq_u32_e32 vcc, v82, v90
	s_nop 1
	v_cndmask_b32_e32 v83, 0, v83, vcc
	v_or_b32_e32 v89, v89, v83
	v_ashrrev_i32_e32 v82, 5, v57
	v_lshlrev_b32_e64 v83, v57, 1
	v_cmp_eq_u32_e32 vcc, v82, v90
	s_nop 1
	v_cndmask_b32_e32 v83, 0, v83, vcc
	v_or_b32_e32 v89, v89, v83
	s_waitcnt lgkmcnt(1)
	v_ashrrev_i32_e32 v82, 5, v58
	v_lshlrev_b32_e64 v83, v58, 1
	v_cmp_eq_u32_e32 vcc, v82, v90
	s_nop 1
	v_cndmask_b32_e32 v83, 0, v83, vcc
	v_or_b32_e32 v89, v89, v83
	v_ashrrev_i32_e32 v82, 5, v59
	v_lshlrev_b32_e64 v83, v59, 1
	v_cmp_eq_u32_e32 vcc, v82, v90
	s_nop 1
	v_cndmask_b32_e32 v83, 0, v83, vcc
	v_or_b32_e32 v89, v89, v83
	v_ashrrev_i32_e32 v82, 5, v60
	v_lshlrev_b32_e64 v83, v60, 1
	v_cmp_eq_u32_e32 vcc, v82, v90
	s_nop 1
	v_cndmask_b32_e32 v83, 0, v83, vcc
	v_or_b32_e32 v89, v89, v83
	v_ashrrev_i32_e32 v82, 5, v61
	v_lshlrev_b32_e64 v83, v61, 1
	v_cmp_eq_u32_e32 vcc, v82, v90
	s_nop 1
	v_cndmask_b32_e32 v83, 0, v83, vcc
	v_or_b32_e32 v89, v89, v83
	s_waitcnt lgkmcnt(0)
	v_ashrrev_i32_e32 v82, 5, v62
	v_lshlrev_b32_e64 v83, v62, 1
	v_cmp_eq_u32_e32 vcc, v82, v90
	s_nop 1
	v_cndmask_b32_e32 v83, 0, v83, vcc
	v_or_b32_e32 v89, v89, v83
	v_ashrrev_i32_e32 v82, 5, v63
	v_lshlrev_b32_e64 v83, v63, 1
	v_cmp_eq_u32_e32 vcc, v82, v90
	s_nop 1
	v_cndmask_b32_e32 v83, 0, v83, vcc
	v_or_b32_e32 v89, v89, v83
	v_ashrrev_i32_e32 v82, 5, v64
	v_lshlrev_b32_e64 v83, v64, 1
	v_cmp_eq_u32_e32 vcc, v82, v90
	s_nop 1
	v_cndmask_b32_e32 v83, 0, v83, vcc
	v_or_b32_e32 v89, v89, v83
	v_ashrrev_i32_e32 v82, 5, v65
	v_lshlrev_b32_e64 v83, v65, 1
	v_cmp_eq_u32_e32 vcc, v82, v90
	s_nop 1
	v_cndmask_b32_e32 v83, 0, v83, vcc
	v_or_b32_e32 v89, v89, v83
	s_branch .Lnsa_mdone_2

; #define LAS __attribute__((address_space(3)))
; template <int MODE> ...
;     const int r16 = lane & 15, q4 = lane >> 4, b = bg >> 2, g = bg & 3;
;     const bf16_t* Kt = KV + (MODE ? 4 : 2) * (size_t)MTOK * 256 + (size_t)bg * SEQ * 64; const bf16_t* Vt = KV + (MODE ? 5 : 3) * (size_t)MTOK * 256 + (size_t)bg * 64 * SEQ;
;     const LAS float* bt = btab + q4 * 1028;
;     const float bfar = bt[1024];
;     const f32x4 z4 = {0.f, 0.f, 0.f, 0.f};
;     const int j0 = MODE ? (qb - 8 > 0 ? qb - 8 : 0) : 0;
;     ...
;     const int srow = tid >> 3, sch = tid & 7, soff = srow * 72 + sch * 8;
;     const unsigned kgo = (unsigned)(srow * 64 + sch * 8) * 2u, vgo = (unsigned)(srow * SEQ + sch * 8) * 2u;
.Lnsa_mskip_3:
	s_nop 0
	s_or_b64 exec, exec, s[20:21]
	v_and_b32_e32 v82, 15, v184
	v_lshrrev_b32_e32 v83, 4, v184
	v_and_b32_e32 v84, 3, v82
	v_lshrrev_b32_e32 v85, 2, v82
	v_and_b32_e32 v86, 1, v85
	v_xor_b32_e32 v87, v83, v84
	v_lshlrev_b32_e32 v87, 4, v87
	v_lshl_add_u32 v87, v86, 6, v87
	v_lshl_add_u32 v88, v85, 3, v84
	v_lshl_add_u32 v98, v88, 7, v87
	v_add_u32_e32 v98, 0xdc40, v98
	v_lshl_add_u32 v99, v82, 7, v87
	v_add_u32_e32 v99, 0xfc40, v99
	v_lshlrev_b32_e32 v88, 7, v86
	v_sub_u32_e32 v0, 64, v88
	v_add_u32_e32 v88, s80, v84
	v_lshlrev_b32_e32 v89, 3, v83
	v_sub_u32_e32 v176, v88, v89
	v_mul_u32_u24_e32 v92, 0x1010, v85
	v_lshl_add_u32 v177, v176, 2, v92
	v_add_u32_e32 v177, 0xffffff64, v177
	ds_read_b32 v225, v92 offset:4096
	v_mov_b32_e32 v252, 0xf149f2ca
	v_min_u32_e32 v82, 39, v184
	v_lshlrev_b32_e32 v82, 2, v82
	v_add_u32_e32 v82, 0x1fd60, v82
	ds_write_b32 v82, v252
	v_mov_b32_e32 v226, 0x1fd60
	s_mov_b32 s54, 0
	s_waitcnt lgkmcnt(0)
	s_barrier

; #define NSA_LD1(jj) do { kr = *(const bf16x8*)((const char*)Kt + (size_t)(jj) * 8192 + kgo); vr = *(const bf16x8*)((const char*)Vt + (jj) * 128 + vgo); } while (0)
; #define NSA_ST1(st_, half_) do { LAS bf16_t* nx_ = stage + (st_) * 18432 + (half_) * 9216 + soff; *(LAS bf16x8*)nx_ = kr; *(LAS bf16x8*)(nx_ + 4608) = vr; } while (0)
; template <int MODE> ...
;     ...
;     f32x4 os[2][4]; float ls[2][4];
; #pragma unroll
;     for (int tile = 0; tile < 2; ++tile)
; #pragma unroll
;         for (int i = 0; i < 4; ++i) { os[tile][i] = z4; ls[tile][i] = 0.f; }
;     const int srow = tid >> 3, sch = tid & 7, soff = srow * 72 + sch * 8;
;     const unsigned kgo = (unsigned)(srow * 64 + sch * 8) * 2u, vgo = (unsigned)(srow * SEQ + sch * 8) * 2u;
;     ...
;     bf16x8 kr, vr;
;     NSA_LD1(j0); NSA_ST1(0, 0);
;     if (j0 + 1 <= qb) { NSA_LD1(j0 + 1); NSA_ST1(0, 1); }
;     __syncthreads();
.Lnsa_kvj_7:
	s_lshr_b32 s15, s97, 13
	s_lshl_b32 s15, s15, 2
	s_and_b32 s1, s88, 3
	s_or_b32 s15, s15, s1
	s_lshl_b32 s15, s15, 20
	s_add_u32 s66, s66, s15
	s_addc_u32 s67, s67, 0
	s_add_u32 s68, s68, s15
	s_addc_u32 s69, s69, 0
	s_lshl_b32 s33, s80, 7
	s_add_i32 s33, s33, 56384
	s_mov_b32 s57, 0
	v_mov_b32_e32 v2, 0
	v_mov_b32_e32 v3, 0
	v_mov_b32_e32 v4, 0
	v_mov_b32_e32 v5, 0
	v_mov_b32_e32 v6, 0
	v_mov_b32_e32 v7, 0
	v_mov_b32_e32 v8, 0
	v_mov_b32_e32 v9, 0
	v_mov_b32_e32 v10, 0
	v_mov_b32_e32 v11, 0
	v_mov_b32_e32 v12, 0
	v_mov_b32_e32 v13, 0
	v_mov_b32_e32 v14, 0
	v_mov_b32_e32 v15, 0
	v_mov_b32_e32 v16, 0
	v_mov_b32_e32 v17, 0
	v_mov_b32_e32 v215, 0
	v_mov_b32_e32 v18, 0
	v_mov_b32_e32 v19, 0
	v_mov_b32_e32 v20, 0
	v_mov_b32_e32 v21, 0
	v_mov_b32_e32 v22, 0
	v_mov_b32_e32 v23, 0
	v_mov_b32_e32 v24, 0
	v_mov_b32_e32 v25, 0
	v_mov_b32_e32 v26, 0
	v_mov_b32_e32 v27, 0
	v_mov_b32_e32 v28, 0
	v_mov_b32_e32 v29, 0
	v_mov_b32_e32 v30, 0
	v_mov_b32_e32 v31, 0
	v_mov_b32_e32 v32, 0
	v_mov_b32_e32 v33, 0
	v_mov_b32_e32 v224, 0
	s_waitcnt lgkmcnt(0)
	v_readlane_b32 s0, v179, s57
	v_readlane_b32 s1, v228, s57
	s_cmp_lt_u32 s57, 64
	s_cselect_b32 s93, s0, s1
	s_min_u32 s14, 1, s19
	v_readlane_b32 s0, v179, s14
	v_readlane_b32 s1, v228, s14
	s_cmp_lt_u32 s14, 64
	s_cselect_b32 s94, s0, s1
	s_cmp_lg_u32 s54, 0
	s_cbranch_scc1 .Lnsa_pdma2_8
	s_and_b32 s73, s94, 255
	s_mov_b32 s14, 1
	s_and_b32 s0, s14, 3
	s_lshl_b32 s0, s0, 14
	s_add_i32 s0, s0, s33
	s_lshl_b32 s1, s73, 13
	s_add_u32 s70, s66, s1
	s_addc_u32 s71, s67, 0
	s_mov_b32 m0, s0
	s_lshl_b32 s1, s73, 7
	global_load_lds_dwordx4 v174, s[70:71]
	s_add_u32 s70, s68, s1
	s_addc_u32 s71, s69, 0
	s_add_i32 m0, s0, 8192
	s_add_i32 s1, s14, 0
	global_load_lds_dwordx4 v175, s[70:71]
.Lnsa_pdma2_8:
	s_mov_b32 s43, 0
	s_waitcnt vmcnt(2)
	s_barrier

; #define LAS __attribute__((address_space(3)))
; #define NSA_LD1(jj) do { kr = *(const bf16x8*)((const char*)Kt + (size_t)(jj) * 8192 + kgo); vr = *(const bf16x8*)((const char*)Vt + (jj) * 128 + vgo); } while (0)
; #define NSA_ST1(st_, half_) do { LAS bf16_t* nx_ = stage + (st_) * 18432 + (half_) * 9216 + soff; *(LAS bf16x8*)nx_ = kr; *(LAS bf16x8*)(nx_ + 4608) = vr; } while (0)
; template <int MODE> ...
;     ...
;     const bf16_t* Kt = KV + (MODE ? 4 : 2) * (size_t)MTOK * 256 + (size_t)bg * SEQ * 64; const bf16_t* Vt = KV + (MODE ? 5 : 3) * (size_t)MTOK * 256 + (size_t)bg * 64 * SEQ;
;     const LAS float* bt = btab + q4 * 1028;
;     const float bfar = bt[1024];
;     const f32x4 z4 = {0.f, 0.f, 0.f, 0.f};
;     const int j0 = MODE ? (qb - 8 > 0 ? qb - 8 : 0) : 0;
;     ...
;     bf16x8 kr, vr;
;     NSA_LD1(j0); NSA_ST1(0, 0);
;     if (j0 + 1 <= qb) { NSA_LD1(j0 + 1); NSA_ST1(0, 1); }
.Lnsa_pvnone_25:
	s_waitcnt vmcnt(0)
	s_barrier
	s_cmp_lg_u32 s54, 0
	s_cbranch_scc1 .Lnsa_noearly_29
	s_add_u32 s66, s30, 0x35900000
	s_addc_u32 s67, s31, 0
	s_add_u32 s68, s30, 0x36900000
	s_addc_u32 s69, s31, 0
	s_lshr_b32 s15, s97, 13
	s_lshl_b32 s15, s15, 2
	s_and_b32 s1, s88, 3
	s_or_b32 s15, s15, s1
	s_lshl_b32 s15, s15, 20
	s_add_u32 s66, s66, s15
	s_addc_u32 s67, s67, 0
	s_add_u32 s68, s68, s15
	s_addc_u32 s69, s69, 0
	s_lshl_b32 s33, s80, 7
	s_add_i32 s33, s33, 56384
	s_add_i32 s14, s18, -8
	s_max_i32 s14, s14, 0
	s_mov_b32 s15, 0
	s_and_b32 s0, s15, 3
	s_lshl_b32 s0, s0, 14
	s_add_i32 s0, s0, s33
	s_lshl_b32 s1, s14, 13
	s_add_u32 s70, s66, s1
	s_addc_u32 s71, s67, 0
	s_mov_b32 m0, s0
	s_lshl_b32 s1, s14, 7
	global_load_lds_dwordx4 v174, s[70:71]
	s_add_u32 s70, s68, s1
	s_addc_u32 s71, s69, 0
	s_add_i32 m0, s0, 8192
	s_add_i32 s1, s15, 0
	global_load_lds_dwordx4 v175, s[70:71]
	s_add_i32 s14, s14, 1
	s_min_i32 s14, s14, s18
	s_mov_b32 s15, 1
	s_and_b32 s0, s15, 3
	s_lshl_b32 s0, s0, 14
	s_add_i32 s0, s0, s33
	s_lshl_b32 s1, s14, 13
	s_add_u32 s70, s66, s1
	s_addc_u32 s71, s67, 0
	s_mov_b32 m0, s0
	s_lshl_b32 s1, s14, 7
	global_load_lds_dwordx4 v174, s[70:71]
	s_add_u32 s70, s68, s1
	s_addc_u32 s71, s69, 0
	s_add_i32 m0, s0, 8192
	s_add_i32 s1, s15, 0
	global_load_lds_dwordx4 v175, s[70:71]
; __device__ __forceinline__ bf16_t tobf(float x) { return (bf16_t)pk2(x, 0.f); }
; __device__ __forceinline__ float red16(float v) { v += __shfl_xor(v, 1); v += __shfl_xor(v, 2); v += __shfl_xor(v, 4); v += __shfl_xor(v, 8); return v; }
; template <int MODE> ...
;     ...
;     for (int tile = 0; tile < 2; ++tile) { const int t0 = qb * 64 + wave * 8 + tile * 4;
; #pragma unroll
;         for (int tt = 0; tt < 4; ++tt) { const float gs = GN[(size_t)(b * SEQ + t0 + tt) * 48 + (g * 4 + q4) * 3 + (MODE ? 2 : 1)] / red16(ls[tile][tt]);
;             bf16_t* op = ONSA + (size_t)(b * SEQ + t0 + tt) * 1024 + (g * 4 + q4) * 64 + r16;
; #pragma unroll
;             for (int nt = 0; nt < 4; ++nt) op[nt * 16] = tobf(bflo((unsigned)op[nt * 16]) + gs * os[tile][nt][tt]); } }
.Lnsa_noearly_29:
.Lnsa_blk_done:
	s_nop 7
	s_nop 7
	v_and_b32_e32 v66, 15, v184
	v_lshrrev_b32_e32 v67, 4, v184
	v_and_b32_e32 v68, 3, v66
	v_lshrrev_b32_e32 v69, 2, v66
	s_lshl_b32 s0, s18, 6
	s_add_i32 s0, s0, s97
	s_add_i32 s0, s0, s80
	v_add_u32_e32 v70, s0, v68
	s_and_b32 s1, s88, 3
	s_lshl_b32 s1, s1, 2
	v_add_u32_e32 v71, s1, v69
	v_lshlrev_b32_e32 v72, 7, v71
	v_lshl_add_u32 v72, v70, 11, v72
	v_lshl_add_u32 v72, v67, 3, v72
	v_add_u32_e32 v73, 0x2000, v72
	v_mul_u32_u24_e32 v74, 0xc0, v70
	v_mul_u32_u24_e32 v75, 12, v71
	s_lshl_b32 s0, s54, 2
	s_add_i32 s0, s0, 4
	v_add3_u32 v74, v74, v75, s0
	s_add_u32 s70, s30, 0x38310000
	s_addc_u32 s71, s31, 0
	s_add_u32 s14, s30, 0xf900000
	s_addc_u32 s15, s31, 0
	global_load_dword v76, v74, s[70:71] offset:0
	global_load_dword v77, v74, s[70:71] offset:768
	global_load_dwordx2 v[50:51], v72, s[14:15] offset:0
	global_load_dwordx2 v[52:53], v72, s[14:15] offset:32
	global_load_dwordx2 v[54:55], v72, s[14:15] offset:64
	global_load_dwordx2 v[56:57], v72, s[14:15] offset:96
	global_load_dwordx2 v[58:59], v73, s[14:15] offset:0
	global_load_dwordx2 v[60:61], v73, s[14:15] offset:32
	global_load_dwordx2 v[62:63], v73, s[14:15] offset:64
	global_load_dwordx2 v[64:65], v73, s[14:15] offset:96
	v_xor_b32_e32 v78, 16, v184
	v_lshlrev_b32_e32 v78, 2, v78
	v_xor_b32_e32 v79, 32, v184
	v_lshlrev_b32_e32 v79, 2, v79
	ds_bpermute_b32 v237, v78, v215
	s_waitcnt lgkmcnt(0)
	v_add_f32_e32 v236, v215, v237
	ds_bpermute_b32 v237, v79, v236
	s_waitcnt lgkmcnt(0)
	v_add_f32_e32 v236, v236, v237
	ds_bpermute_b32 v245, v78, v224
	s_waitcnt lgkmcnt(0)
	v_add_f32_e32 v244, v224, v245
	ds_bpermute_b32 v245, v79, v244
	s_waitcnt lgkmcnt(0)
	v_add_f32_e32 v244, v244, v245
	s_waitcnt vmcnt(9)
	v_div_scale_f32 v237, s[20:21], v236, v236, v76
	v_rcp_f32_e32 v238, v237
	v_div_scale_f32 v239, vcc, v76, v236, v76
	v_fma_f32 v240, -v237, v238, 1.0
	v_fmac_f32_e32 v238, v240, v238
	v_mul_f32_e32 v240, v239, v238
	v_fma_f32 v241, -v237, v240, v239
	v_fmac_f32_e32 v240, v241, v238
	v_fma_f32 v237, -v237, v240, v239
	s_nop 1
	v_div_fmas_f32 v237, v237, v238, v240
	v_div_fixup_f32 v239, v237, v236, v76
	s_waitcnt vmcnt(8)
	v_div_scale_f32 v245, s[20:21], v244, v244, v77
	v_rcp_f32_e32 v246, v245
	v_div_scale_f32 v247, vcc, v77, v244, v77
	v_fma_f32 v248, -v245, v246, 1.0
	v_fmac_f32_e32 v246, v248, v246
	v_mul_f32_e32 v248, v247, v246
	v_fma_f32 v249, -v245, v248, v247
	v_fmac_f32_e32 v248, v249, v246
	v_fma_f32 v245, -v245, v248, v247
	s_nop 1
	v_div_fmas_f32 v245, v245, v246, v248
	v_div_fixup_f32 v247, v245, v244, v77
	s_waitcnt vmcnt(7)
	v_lshlrev_b32_e32 v242, 16, v50
	v_and_b32_e32 v243, 0xffff0000, v50
	v_fmac_f32_e32 v242, v239, v2
	v_fmac_f32_e32 v243, v239, v3
	v_cvt_pk_bf16_f32 v82, v242, v243
	v_lshlrev_b32_e32 v242, 16, v51
	v_and_b32_e32 v243, 0xffff0000, v51
	v_fmac_f32_e32 v242, v239, v4
	v_fmac_f32_e32 v243, v239, v5
	v_cvt_pk_bf16_f32 v83, v242, v243
	s_waitcnt vmcnt(6)
	v_lshlrev_b32_e32 v242, 16, v52
	v_and_b32_e32 v243, 0xffff0000, v52
	v_fmac_f32_e32 v242, v239, v6
	v_fmac_f32_e32 v243, v239, v7
	v_cvt_pk_bf16_f32 v84, v242, v243
	v_lshlrev_b32_e32 v242, 16, v53
	v_and_b32_e32 v243, 0xffff0000, v53
	v_fmac_f32_e32 v242, v239, v8
	v_fmac_f32_e32 v243, v239, v9
	v_cvt_pk_bf16_f32 v85, v242, v243
	s_waitcnt vmcnt(5)
	v_lshlrev_b32_e32 v242, 16, v54
	v_and_b32_e32 v243, 0xffff0000, v54
	v_fmac_f32_e32 v242, v239, v10
	v_fmac_f32_e32 v243, v239, v11
	v_cvt_pk_bf16_f32 v86, v242, v243
	v_lshlrev_b32_e32 v242, 16, v55
	v_and_b32_e32 v243, 0xffff0000, v55
	v_fmac_f32_e32 v242, v239, v12
	v_fmac_f32_e32 v243, v239, v13
	v_cvt_pk_bf16_f32 v87, v242, v243
	s_waitcnt vmcnt(4)
	v_lshlrev_b32_e32 v242, 16, v56
	v_and_b32_e32 v243, 0xffff0000, v56
	v_fmac_f32_e32 v242, v239, v14
	v_fmac_f32_e32 v243, v239, v15
	v_cvt_pk_bf16_f32 v88, v242, v243
	v_lshlrev_b32_e32 v242, 16, v57
	v_and_b32_e32 v243, 0xffff0000, v57
	v_fmac_f32_e32 v242, v239, v16
	v_fmac_f32_e32 v243, v239, v17
	v_cvt_pk_bf16_f32 v89, v242, v243
	s_waitcnt vmcnt(3)
	v_lshlrev_b32_e32 v250, 16, v58
	v_and_b32_e32 v251, 0xffff0000, v58
	v_fmac_f32_e32 v250, v247, v18
	v_fmac_f32_e32 v251, v247, v19
	v_cvt_pk_bf16_f32 v90, v250, v251
	v_lshlrev_b32_e32 v250, 16, v59
	v_and_b32_e32 v251, 0xffff0000, v59
	v_fmac_f32_e32 v250, v247, v20
	v_fmac_f32_e32 v251, v247, v21
	v_cvt_pk_bf16_f32 v91, v250, v251
	s_waitcnt vmcnt(2)
	v_lshlrev_b32_e32 v250, 16, v60
	v_and_b32_e32 v251, 0xffff0000, v60
	v_fmac_f32_e32 v250, v247, v22
	v_fmac_f32_e32 v251, v247, v23
	v_cvt_pk_bf16_f32 v92, v250, v251
	v_lshlrev_b32_e32 v250, 16, v61
	v_and_b32_e32 v251, 0xffff0000, v61
	v_fmac_f32_e32 v250, v247, v24
	v_fmac_f32_e32 v251, v247, v25
	v_cvt_pk_bf16_f32 v93, v250, v251
	s_waitcnt vmcnt(1)
	v_lshlrev_b32_e32 v250, 16, v62
	v_and_b32_e32 v251, 0xffff0000, v62
	v_fmac_f32_e32 v250, v247, v26
	v_fmac_f32_e32 v251, v247, v27
	v_cvt_pk_bf16_f32 v94, v250, v251
	v_lshlrev_b32_e32 v250, 16, v63
	v_and_b32_e32 v251, 0xffff0000, v63
	v_fmac_f32_e32 v250, v247, v28
	v_fmac_f32_e32 v251, v247, v29
	v_cvt_pk_bf16_f32 v95, v250, v251
	s_waitcnt vmcnt(0)
	v_lshlrev_b32_e32 v250, 16, v64
	v_and_b32_e32 v251, 0xffff0000, v64
	v_fmac_f32_e32 v250, v247, v30
	v_fmac_f32_e32 v251, v247, v31
	v_cvt_pk_bf16_f32 v96, v250, v251
	v_lshlrev_b32_e32 v250, 16, v65
	v_and_b32_e32 v251, 0xffff0000, v65
	v_fmac_f32_e32 v250, v247, v32
	v_fmac_f32_e32 v251, v247, v33
	v_cvt_pk_bf16_f32 v97, v250, v251
	global_store_dwordx2 v72, v[82:83], s[14:15] offset:0
	global_store_dwordx2 v72, v[84:85], s[14:15] offset:32
	global_store_dwordx2 v72, v[86:87], s[14:15] offset:64
	global_store_dwordx2 v72, v[88:89], s[14:15] offset:96
	global_store_dwordx2 v73, v[90:91], s[14:15] offset:0
	global_store_dwordx2 v73, v[92:93], s[14:15] offset:32
	global_store_dwordx2 v73, v[94:95], s[14:15] offset:64
	global_store_dwordx2 v73, v[96:97], s[14:15] offset:96
	s_waitcnt vmcnt(0)
	s_add_i32 s54, s54, 1
	s_cmp_eq_u32 s54, 1
	s_cbranch_scc1 .Lnsa_mode_top
	v_cmp_gt_u32_e32 vcc, 0x44, v183
	s_nop 0
	s_and_saveexec_b64 s[20:21], vcc
	s_cbranch_execz .Lnsa_zskip_30
	v_lshlrev_b32_e32 v50, 2, v183
	v_add_u32_e32 v50, 0x1fc40, v50
	ds_write_b32 v50, v1
